# P3 panel-counter poll: four polls in flight (ring) instead of one round trip per retry
# baseline (speedup 1.0000x reference)
; __device__ __forceinline__ unsigned xb_ld(unsigned* p)              { return __hip_atomic_load(p, __ATOMIC_RELAXED, __HIP_MEMORY_SCOPE_AGENT); }
; #define XB_SPIN(cond, bar) do { unsigned _sp = 0; while (cond) { __builtin_amdgcn_s_sleep(1); \
;     if ((++_sp & 255u) == 0u) { if (xb_ld(&(bar)[XB_TMO])) break; if (_sp > XB_SPIN_CAP) { atomicAdd(&(bar)[XB_TMO], 1u); break; } } } } while (0)
; __global__ void __launch_bounds__(NTHR, 2) k_main(Args a) {
;     ...
;         if (tid == 0) {
;             int plo = 0, phi = T / 256 - 1;
;             if (nb == 256) { const int r0 = min(max(64 * bid - 128, 0), max(128 * (bid >> 1) - 3, 0)), r1 = max(64 * bid + 63, 128 * (bid >> 1) + 127); plo = r0 >> 8; phi = r1 >> 8; }
;             for (int p = plo; p <= phi; ++p) { unsigned* cw = &((unsigned*)ws)[8192 + 16 * p]; XB_SPIN(xb_ld(cw) < (unsigned)(PS / 256), (unsigned*)ws); }
;             __builtin_amdgcn_fence(__ATOMIC_ACQUIRE, "agent");
;             asm volatile("s_waitcnt vmcnt(0)" ::: "memory");
;         }
.LBB0_154:
	s_lshl_b32 s4, s3, 4
	s_lshl_b64 s[6:7], s[4:5], 2
	s_add_u32 s6, s90, s6
	s_addc_u32 s7, s91, s7
	global_load_dword v3, v1, s[6:7] sc1
	s_add_u32 s6, s6, 0x8000
	s_addc_u32 s7, s7, 0
	s_waitcnt vmcnt(0)
	v_cmp_lt_u32_e32 vcc, 8, v3
	s_cbranch_vccnz .LBB0_153
	s_movk_i32 s4, 0x1000
	global_load_dword v236, v2, s[6:7] sc1
	s_sleep 3
	global_load_dword v237, v2, s[6:7] sc1
	s_sleep 3
	global_load_dword v238, v2, s[6:7] sc1
	s_sleep 3
.Lp3_ring:
	global_load_dword v239, v2, s[6:7] sc1
	s_waitcnt vmcnt(3)
	v_cmp_lt_u32_e32 vcc, 8, v236
	s_cbranch_vccnz .Lp3_ring_ok
	global_load_dword v236, v2, s[6:7] sc1
	s_waitcnt vmcnt(3)
	v_cmp_lt_u32_e32 vcc, 8, v237
	s_cbranch_vccnz .Lp3_ring_ok
	global_load_dword v237, v2, s[6:7] sc1
	s_waitcnt vmcnt(3)
	v_cmp_lt_u32_e32 vcc, 8, v238
	s_cbranch_vccnz .Lp3_ring_ok
	global_load_dword v238, v2, s[6:7] sc1
	s_waitcnt vmcnt(3)
	v_cmp_lt_u32_e32 vcc, 8, v239
	s_cbranch_vccnz .Lp3_ring_ok
	s_sub_i32 s4, s4, 1
	s_cmp_lg_u32 s4, 0
	s_cbranch_scc1 .Lp3_ring
	s_waitcnt vmcnt(0)
	s_mov_b32 s4, 1
	s_branch .LBB0_157
.Lp3_ring_ok:
	s_waitcnt vmcnt(0)
	s_branch .LBB0_153

; #define LAS __attribute__((address_space(3)))
; __global__ void __launch_bounds__(NTHR, 2) k_main(Args a) {
;     ...
;             for (int i = tid; i < 2 * 128 * 8; i += NTHR) {
;                 const int pc = i & 7, key = (i >> 3) & 127, hf = (i >> 10) & 1, hl = i >> 11;
;                 *(LAS v4u*)(KHL + ((hl * 2 + hf) * 128 + key) * 72 + pc * 8) = *(const v4u*)((hl ? KL : KH) + (size_t)(hf * 128 + key) * 64 + pc * 8);
;             }
.LBB0_665:
	v_mov_b32_e32 v20, s53
	v_mov_b32_e32 v21, s49
	v_mov_b32_e32 v22, s52
	v_mov_b32_e32 v23, s48
	v_lshlrev_b32_e32 v24, 4, v19
	v_cmp_gt_u32_e32 vcc, s54, v19
	v_lshlrev_b32_e32 v25, 1, v18
	v_and_b32_e32 v82, 0x7f80, v24
	v_cndmask_b32_e32 v21, v20, v21, vcc
	v_cndmask_b32_e32 v20, v22, v23, vcc
	v_lshl_add_u64 v[20:21], v[20:21], 0, v[82:83]
	v_and_b32_e32 v82, 0x70, v25
	v_lshl_add_u64 v[20:21], v[20:21], 0, v[82:83]
	global_load_dwordx4 v[162:165], v[20:21], off
	v_lshrrev_b32_e32 v24, 3, v19
	v_mul_lo_u32 v24, v24, s56
	v_add3_u32 v178, 0, v24, v82
	v_add_u32_e32 v19, 0x200, v19
	v_add_u32_e32 v18, 0x1000, v18
	v_mov_b32_e32 v20, s53
	v_mov_b32_e32 v21, s49
	v_mov_b32_e32 v22, s52
	v_mov_b32_e32 v23, s48
	v_lshlrev_b32_e32 v24, 4, v19
	v_cmp_gt_u32_e32 vcc, s54, v19
	v_lshlrev_b32_e32 v25, 1, v18
	v_and_b32_e32 v82, 0x7f80, v24
	v_cndmask_b32_e32 v21, v20, v21, vcc
	v_cndmask_b32_e32 v20, v22, v23, vcc
	v_lshl_add_u64 v[20:21], v[20:21], 0, v[82:83]
	v_and_b32_e32 v82, 0x70, v25
	v_lshl_add_u64 v[20:21], v[20:21], 0, v[82:83]
	global_load_dwordx4 v[166:169], v[20:21], off
	v_lshrrev_b32_e32 v24, 3, v19
	v_mul_lo_u32 v24, v24, s56
	v_add3_u32 v179, 0, v24, v82
	v_add_u32_e32 v19, 0x200, v19
	v_add_u32_e32 v18, 0x1000, v18
	v_mov_b32_e32 v20, s53
	v_mov_b32_e32 v21, s49
	v_mov_b32_e32 v22, s52
	v_mov_b32_e32 v23, s48
	v_lshlrev_b32_e32 v24, 4, v19
	v_cmp_gt_u32_e32 vcc, s54, v19
	v_lshlrev_b32_e32 v25, 1, v18
	v_and_b32_e32 v82, 0x7f80, v24
	v_cndmask_b32_e32 v21, v20, v21, vcc
	v_cndmask_b32_e32 v20, v22, v23, vcc
	v_lshl_add_u64 v[20:21], v[20:21], 0, v[82:83]
	v_and_b32_e32 v82, 0x70, v25
	v_lshl_add_u64 v[20:21], v[20:21], 0, v[82:83]
	global_load_dwordx4 v[170:173], v[20:21], off
	v_lshrrev_b32_e32 v24, 3, v19
	v_mul_lo_u32 v24, v24, s56
	v_add3_u32 v180, 0, v24, v82
	v_add_u32_e32 v19, 0x200, v19
	v_add_u32_e32 v18, 0x1000, v18
	v_mov_b32_e32 v20, s53
	v_mov_b32_e32 v21, s49
	v_mov_b32_e32 v22, s52
	v_mov_b32_e32 v23, s48
	v_lshlrev_b32_e32 v24, 4, v19
	v_cmp_gt_u32_e32 vcc, s54, v19
	v_lshlrev_b32_e32 v25, 1, v18
	v_and_b32_e32 v82, 0x7f80, v24
	v_cndmask_b32_e32 v21, v20, v21, vcc
	v_cndmask_b32_e32 v20, v22, v23, vcc
	v_lshl_add_u64 v[20:21], v[20:21], 0, v[82:83]
	v_and_b32_e32 v82, 0x70, v25
	v_lshl_add_u64 v[20:21], v[20:21], 0, v[82:83]
	global_load_dwordx4 v[174:177], v[20:21], off
	v_lshrrev_b32_e32 v24, 3, v19
	v_mul_lo_u32 v24, v24, s56
	v_add3_u32 v181, 0, v24, v82
	v_add_u32_e32 v19, 0x200, v19
	v_add_u32_e32 v18, 0x1000, v18
	s_waitcnt vmcnt(0)
	ds_write_b128 v178, v[162:165]
	ds_write_b128 v179, v[166:169]
	ds_write_b128 v180, v[170:173]
	ds_write_b128 v181, v[174:177]
	s_nop 0
	s_nop 0
	s_nop 0
	s_nop 0
	s_nop 0
	s_nop 0
	s_nop 0
	s_nop 0
	s_nop 0
	s_nop 0
	s_nop 0
	s_nop 0
	s_nop 0
	s_nop 0
	s_nop 0
	s_nop 0
	s_nop 0
	s_nop 0
	s_nop 0
	s_nop 0
	s_nop 0
	s_nop 0
	s_nop 0
